# tail balancing: second of the two barrier-free MLA up-projection GEMMs walks CUs in reverse order (max tiles per CU 5 -> 4), on top of v018
# baseline (speedup 1.0000x reference)
;     __host__ __device__ bool next(int i, Unit& u) const {
;         const long L = (long)i * G + c; if (L >= nwg) return false;
;         int wgid = (int)L; { const int q = nwg / NXCD, r = nwg % NXCD, xcd = wgid % NXCD, off = wgid / NXCD; wgid = (xcd < r ? xcd * (q + 1) : r * (q + 1) + (xcd - r) * q) + off; }
;         const int nig = WGM * nN, gid = wgid / nig, fm = gid * WGM, gsz = (nM - fm) < WGM ? (nM - fm) : WGM;
;         u.pm = fm + ((wgid % nig) % gsz); u.pn = (wgid % nig) / gsz; return true;
;     }
; template <class Epi, class Sched, bool ALIGN_EPI = false, bool SP2 = false>
; __device__ __forceinline__ void gemm_phase(PG8_LAS unsigned char* lds, const Gemm g, const Sched& S, const Epi& E, const int wave0) {
;     const int tid = fresh_tid(wave0), wid = __builtin_amdgcn_readfirstlane(tid >> 6), lane = tid & 63, wr = wid >> 2, wc = wid & 3, fr = lane & 15, fq = lane >> 4;
;     const int K = g.K, nt = K / BK;
;     const unsigned ldsb0 = (unsigned)(uintptr_t)lds;
;     unsigned voffA[2], voffB[2];
; #pragma unroll
;     for (int i = 0; i < 2; ++i) { int R, C; stage_rc(tid * 16 + i * 8192, R, C); const int Rb = Epi::PERM ? ((R & ~31) + perm32(R & 31)) : R;
;         voffA[i] = (unsigned)(R * g.lda + C) * 2u; voffB[i] = (unsigned)(Rb * g.ldb + C) * 2u; }
;     const size_t kstep = (size_t)(BK * 2);
;     const size_t hstepA = (size_t)HALF * g.lda * 2, hstepB = (size_t)HALF * g.ldb * 2; const size_t ksb = (size_t)K * 2;
;     ...
;     const size_t tstepA = 2 * hstepA, tstepB = 2 * hstepB;
;     const unsigned ldsw = (unsigned)wid * 1024u;
;     const int aoff = lds_byte(wr * 64 + fr, fq * 8), boff = lds_byte(wc * 32 + fr, fq * 8);
;     ...
;     Unit cur, nxt; int ui = 0;
;     if (!S.next(0, cur)) return;
;     f32x4 acc[2][2][4][2];
; #pragma unroll
;     for (int a = 0; a < 2; ++a)
; #pragma unroll
;         for (int b = 0; b < 2; ++b)
; #pragma unroll
;             for (int m = 0; m < 4; ++m)
; #pragma unroll
;                 for (int n = 0; n < 2; ++n) acc[a][b][m][n] = (f32x4){0.f, 0.f, 0.f, 0.f};
;     bf16x8 At[4][2], B0[2][2], B1[2][2];
;     const char* cA = PG8_APTR(cur); const char* cB = PG8_BPTR(cur);
;     S.a_ready(cur);
;     if constexpr (SP2) {
;         PG8_STAGE(PG8_SB(0, 0), cB, voffB); PG8_STAGE(PG8_SB(0, 1), cB + hstepB, voffB); PG8_STAGE(PG8_SA(0, 0), cA, voffA); PG8_STAGE(PG8_SA(0, 1), cA + hstepA, voffA);
;         if (wr == 1) PG8_BAR;
.LBB0_642:
	s_sub_i32 s11, 0xff, s87
	s_and_b64 s[4:5], s[18:19], exec
	s_movk_i32 s2, 0x600
	s_cselect_b32 s2, s2, 0x800
	s_cselect_b32 s11, s11, s87
	s_lshr_b32 s4, s2, 8
	s_mul_i32 s30, s4, 0x42
	v_mbcnt_lo_u32_b32 v0, -1, 0
	v_mbcnt_hi_u32_b32 v0, -1, v0
	s_cmp_ge_i32 s11, s30
	v_add_u32_e32 v1, s93, v0
	s_nop 0
	v_readfirstlane_b32 s6, v1
	s_cbranch_scc1 .LBB0_637
	v_ashrrev_i32_e32 v3, 31, v1
	v_lshrrev_b32_e32 v3, 26, v3
	v_lshlrev_b32_e32 v2, 4, v1
	v_add_u32_e32 v3, v1, v3
	v_bfe_i32 v1, v1, 27, 1
	v_lshrrev_b32_e32 v1, 22, v1
	v_add_u32_e32 v1, v2, v1
	v_and_b32_e32 v1, 0xfffffc00, v1
	v_sub_u32_e32 v1, v2, v1
	v_lshrrev_b32_e32 v4, 4, v1
	v_bitop3_b32 v1, v4, v1, 32 bitop3:0x6c
	v_ashrrev_i32_e32 v5, 31, v1
	v_lshrrev_b32_e32 v5, 26, v5
	v_ashrrev_i32_e32 v3, 6, v3
	v_add_u32_e32 v5, v1, v5
	v_lshlrev_b32_e32 v4, 3, v3
	v_ashrrev_i32_e32 v6, 6, v5
	v_and_b32_e32 v5, 0xc0, v5
	v_and_b32_e32 v4, -16, v4
	v_lshlrev_b32_e32 v3, 5, v3
	v_sub_u32_e32 v1, v1, v5
	v_add_u32_e32 v4, v6, v4
	v_and_b32_e32 v3, 32, v3
	v_ashrrev_i16_sdwa v1, v251, sext(v1) dst_sel:DWORD dst_unused:UNUSED_PAD src0_sel:DWORD src1_sel:BYTE_0
	v_add_u32_sdwa v1, v3, sext(v1) dst_sel:DWORD dst_unused:UNUSED_PAD src0_sel:DWORD src1_sel:WORD_0
	v_lshlrev_b32_e32 v3, 1, v4
	v_lshrrev_b32_e32 v5, 2, v4
	v_and_b32_e32 v6, 3, v6
	s_mov_b32 s9, 0x3fffe0
	s_movk_i32 s8, 0xb00
	v_and_b32_e32 v3, 24, v3
	v_and_b32_e32 v5, 4, v5
	v_and_or_b32 v6, v4, s9, v6
	v_mul_lo_u32 v4, v4, s8
	v_or3_b32 v3, v6, v5, v3
	v_add_lshl_u32 v130, v1, v4, 1
	v_lshlrev_b32_e32 v1, 1, v1
	v_lshl_add_u32 v131, v3, 10, v1
	v_add_u32_e32 v1, 0x2000, v2
	v_ashrrev_i32_e32 v2, 31, v1
	v_lshrrev_b32_e32 v2, 22, v2
	v_add_u32_e32 v2, v1, v2
	v_ashrrev_i32_e32 v2, 10, v2
	v_mul_i32_i24_e32 v3, 0x400, v2
	v_sub_u32_e32 v1, v1, v3
	v_lshrrev_b32_e32 v3, 4, v1
	v_bitop3_b32 v1, v3, v1, 32 bitop3:0x6c
	v_ashrrev_i32_e32 v4, 31, v1
	v_lshrrev_b32_e32 v4, 26, v4
	v_add_u32_e32 v4, v1, v4
	v_lshlrev_b32_e32 v3, 3, v2
	v_ashrrev_i32_e32 v5, 6, v4
	v_and_b32_e32 v4, 0xc0, v4
	v_and_b32_e32 v3, -16, v3
	v_lshlrev_b32_e32 v2, 5, v2
	v_sub_u32_e32 v1, v1, v4
	v_add_u32_e32 v3, v5, v3
	v_and_b32_e32 v2, 32, v2
	v_ashrrev_i16_sdwa v1, v251, sext(v1) dst_sel:DWORD dst_unused:UNUSED_PAD src0_sel:DWORD src1_sel:BYTE_0
	s_lshr_b32 s5, s30, 3
	s_ashr_i32 s7, s6, 6
	v_add_u32_sdwa v1, v2, sext(v1) dst_sel:DWORD dst_unused:UNUSED_PAD src0_sel:DWORD src1_sel:WORD_0
	v_lshlrev_b32_e32 v2, 1, v3
	v_lshrrev_b32_e32 v4, 2, v3
	v_and_b32_e32 v5, 3, v5
	s_and_b32 s54, s30, 4
	s_add_i32 s55, s5, 1
	s_lshr_b32 s56, s2, 5
	v_and_b32_e32 v2, 24, v2
	v_and_b32_e32 v4, 4, v4
	v_and_or_b32 v5, v3, s9, v5
	v_mul_lo_u32 v3, v3, s8
	s_ashr_i32 s44, s6, 8
	s_lshl_b32 s45, s7, 10
	s_lshl_b32 s8, s2, 1
	v_or3_b32 v2, v5, v4, v2
	v_add_lshl_u32 v132, v1, v3, 1
	v_lshlrev_b32_e32 v1, 1, v1
	s_waitcnt lgkmcnt(0)
	s_add_u32 s8, s42, s8
	v_lshl_add_u32 v133, v2, 10, v1
	s_addc_u32 s9, s43, 0
	v_cvt_f32_ubyte0_e32 v1, s56
	s_add_u32 s58, s8, 0x13e00000
	v_rcp_iflag_f32_e32 v1, v1
	s_addc_u32 s59, s9, 0
	s_and_b64 s[8:9], s[18:19], exec
	s_cselect_b32 s8, s84, 0xe00000
	s_add_u32 s60, s40, s8
	v_readlane_b32 s18, v254, 15
	v_mul_f32_e32 v1, 0x4f7ffffe, v1
	s_addc_u32 s61, s41, 0
	s_sub_i32 s9, s18, s54
	v_cvt_u32_f32_e32 v1, v1
	s_mul_i32 s57, s55, s54
	s_mul_i32 s9, s9, s5
	s_add_i32 s9, s9, s57
	s_mul_i32 s8, s55, s18
	s_cmp_lt_i32 s18, s54
	s_cselect_b32 s8, s8, s9
	s_sub_i32 s19, 0, s56
	v_readfirstlane_b32 s62, v1
	v_readlane_b32 s9, v254, 25
	s_mul_i32 s19, s19, s62
	s_add_i32 s8, s8, s9
	s_mul_hi_u32 s19, s62, s19
	s_abs_i32 s18, s8
	s_add_i32 s62, s62, s19
	s_mul_hi_u32 s19, s18, s62
	s_mul_i32 s40, s19, s56
	s_sub_i32 s18, s18, s40
	s_ashr_i32 s9, s8, 31
	s_add_i32 s40, s19, 1
	s_sub_i32 s41, s18, s56
	s_cmp_ge_u32 s18, s56
	s_cselect_b32 s19, s40, s19
	s_cselect_b32 s18, s41, s18
	s_add_i32 s40, s19, 1
	s_cmp_ge_u32 s18, s56
	s_cselect_b32 s18, s40, s19
	s_xor_b32 s18, s18, s9
	s_sub_i32 s9, s18, s9
	s_lshl_b32 s18, s9, 3
	s_sub_i32 s19, 0x42, s18
	s_min_i32 s19, s19, 8
	s_abs_i32 s41, s19
	v_cvt_f32_u32_e32 v1, s41
	s_sub_i32 s42, 0, s41
	s_mul_i32 s9, s9, s56
	s_sub_i32 s8, s8, s9
	v_rcp_iflag_f32_e32 v1, v1
	s_abs_i32 s40, s8
	s_xor_b32 s9, s8, s19
	s_ashr_i32 s9, s9, 31
	v_mul_f32_e32 v1, 0x4f7ffffe, v1
	v_cvt_u32_f32_e32 v1, v1
	v_cvt_f32_ubyte1_e32 v2, s2
	v_rcp_iflag_f32_e32 v3, v2
	s_load_dwordx2 s[38:39], s[38:39], 0xf0
	v_readfirstlane_b32 s43, v1
	s_mul_i32 s42, s42, s43
	s_mul_hi_u32 s42, s43, s42
	s_add_i32 s43, s43, s42
	s_mul_hi_u32 s42, s40, s43
	s_mul_i32 s43, s42, s41
	s_sub_i32 s40, s40, s43
	s_add_i32 s43, s42, 1
	s_sub_i32 s46, s40, s41
	s_cmp_ge_u32 s40, s41
	s_cselect_b32 s42, s43, s42
	s_cselect_b32 s40, s46, s40
	s_add_i32 s43, s42, 1
	s_cmp_ge_u32 s40, s41
	s_cselect_b32 s40, s43, s42
	s_xor_b32 s40, s40, s9
	s_sub_i32 s95, s40, s9
	s_mul_i32 s9, s95, s19
	s_sub_i32 s8, s8, s9
	s_add_i32 s96, s8, s18
	s_sext_i32_i8 s8, s95
	v_cvt_f32_i32_e32 v1, s8
	s_ashr_i32 s9, s8, 30
	s_or_b32 s18, s9, 1
	s_mul_i32 s41, s96, 0x160000
	v_mul_f32_e32 v3, v1, v3
	v_trunc_f32_e32 v3, v3
	v_fma_f32 v1, -v3, v2, v1
	v_cvt_i32_f32_e32 v3, v3
	v_cmp_ge_f32_e64 s[8:9], |v1|, v2
	s_and_b64 s[8:9], s[8:9], exec
	s_cselect_b32 s8, s18, 0
	v_readfirstlane_b32 s9, v3
	s_add_i32 s8, s9, s8
	s_bfe_i64 s[18:19], s[8:9], 0x80000
	s_mul_i32 s8, s8, s4
	s_sub_i32 s8, s95, s8
	s_bfe_i64 s[8:9], s[8:9], 0x80000
	s_lshl_b64 s[18:19], s[18:19], 10
	s_lshl_b64 s[8:9], s[8:9], 18
	s_add_u32 s8, s60, s8
	s_addc_u32 s9, s61, s9
	s_add_u32 s46, s8, s18
	s_addc_u32 s47, s9, s19
	s_add_i32 s63, s45, 0
	s_add_i32 s64, s63, 0x10000
	s_add_i32 s65, s63, 0x12000
	s_mul_hi_i32 s40, s96, 0x160000
	s_add_u32 s41, s58, s41
	s_mov_b32 m0, s64
	s_nop 0
	global_load_lds_dwordx4 v131, s[46:47]
	s_addc_u32 s40, s59, s40
	s_add_i32 s66, s63, 0x14000
	s_mov_b32 m0, s65
	s_nop 0
	global_load_lds_dwordx4 v133, s[46:47]
	s_add_u32 s8, s46, 0x20000
	s_addc_u32 s9, s47, 0
	s_mov_b32 m0, s66
	s_nop 0
	global_load_lds_dwordx4 v131, s[8:9]
	s_add_i32 s67, s63, 0x16000
	s_mov_b32 m0, s67
	s_nop 0
	global_load_lds_dwordx4 v133, s[8:9]
	s_add_u32 s48, s41, s18
	s_addc_u32 s49, s40, s19
	s_mov_b32 m0, s63
	s_nop 0
	global_load_lds_dwordx4 v130, s[48:49]
	s_add_i32 s68, s63, 0x2000
	s_add_i32 s69, s63, 0x4000
	s_mov_b32 m0, s68
	s_nop 0
	global_load_lds_dwordx4 v132, s[48:49]
	s_add_u32 s8, s48, 0xb0000
	s_addc_u32 s9, s49, 0
	s_mov_b32 m0, s69
	s_nop 0
	global_load_lds_dwordx4 v130, s[8:9]
	s_add_i32 s70, s63, 0x6000
	s_mov_b32 m0, s70
	s_nop 0
	global_load_lds_dwordx4 v132, s[8:9]
	s_cmp_eq_u32 s44, 1
	s_cselect_b64 s[18:19], -1, 0
	s_cmp_lg_u32 s44, 1
	s_cbranch_scc1 .LBB0_645
	s_barrier

;     __host__ __device__ bool next(int i, Unit& u) const {
;         const long L = (long)i * G + c; if (L >= nwg) return false;
;         int wgid = (int)L; { const int q = nwg / NXCD, r = nwg % NXCD, xcd = wgid % NXCD, off = wgid / NXCD; wgid = (xcd < r ? xcd * (q + 1) : r * (q + 1) + (xcd - r) * q) + off; }
;         const int nig = WGM * nN, gid = wgid / nig, fm = gid * WGM, gsz = (nM - fm) < WGM ? (nM - fm) : WGM;
;         u.pm = fm + ((wgid % nig) % gsz); u.pn = (wgid % nig) / gsz; return true;
; template <class Epi, class Sched, bool ALIGN_EPI = false, bool SP2 = false>
; __device__ __forceinline__ void gemm_phase(PG8_LAS unsigned char* lds, const Gemm g, const Sched& S, const Epi& E, const int wave0) {
;     ...
;         const bool has_next = S.next(ui + 1, nxt);
;         const char* nA = has_next ? PG8_APTR(nxt) : cA; const char* nB = has_next ? PG8_BPTR(nxt) : cB;
.LBB0_648:
	s_add_i32 s91, s91, 1
	s_mul_i32 s6, s91, s37
	s_mul_hi_u32 s7, s91, s74
	s_add_i32 s7, s7, s6
	s_mul_i32 s6, s91, s74
	s_add_u32 s38, s6, s11
	s_addc_u32 s39, s7, s36
	v_mov_b64_e32 v[0:1], s[30:31]
	v_cmp_ge_i64_e32 vcc, s[38:39], v[0:1]
	v_cmp_lt_i64_e64 s[40:41], s[38:39], v[0:1]
	s_cbranch_vccnz .LBB0_654
	s_ashr_i32 s6, s38, 31
	s_lshr_b32 s6, s6, 29
	s_add_i32 s6, s38, s6
	s_and_b32 s7, s6, -8
	s_sub_i32 s7, s38, s7
	s_cmp_ge_i32 s7, s54
	s_mov_b64 s[38:39], -1
	s_cbranch_scc0 .LBB0_651
	s_sub_i32 s8, s7, s54
	s_mul_i32 s8, s8, s5
	s_add_i32 s44, s8, s57
	s_mov_b64 s[38:39], 0
